# P4d EpiMerge epilogue rewritten: rolling window of 12 loads in flight instead of 32 serialized round trips
# baseline (speedup 1.0000x reference)
.LBB0_540:
	v_lshl_add_u32 v140, s3, 8, v144
	v_lshl_or_b32 v138, s2, 8, v146
	v_ashrrev_i32_e32 v141, 31, v140
	v_ashrrev_i32_e32 v139, 31, v138
	v_lshlrev_b64 v[142:143], 10, v[140:141]
	v_lshl_add_u64 v[142:143], v[142:143], 0, v[138:139]
	v_lshlrev_b64 v[142:143], 1, v[142:143]
	s_mov_b64 s[16:17], -1
	s_andn2_b64 vcc, exec, s[4:5]
	v_mov_b32_e32 v148, v142
	global_load_dwordx4 v[148:151], v148, s[66:67]
	v_mov_b32_e32 v152, v142
	global_load_dwordx4 v[152:155], v152, s[70:71]
	v_mov_b32_e32 v168, v142
	global_load_dwordx4 v[168:171], v168, s[66:67] offset:256
	v_mov_b32_e32 v172, v142
	global_load_dwordx4 v[172:175], v172, s[70:71] offset:256
	v_add_u32_e32 v176, 0x8000, v142
	global_load_dwordx4 v[176:179], v176, s[66:67]
	v_add_u32_e32 v180, 0x8000, v142
	global_load_dwordx4 v[180:183], v180, s[70:71]
	v_add_u32_e32 v184, 0x8000, v142
	global_load_dwordx4 v[184:187], v184, s[66:67] offset:256
	v_add_u32_e32 v188, 0x8000, v142
	global_load_dwordx4 v[188:191], v188, s[70:71] offset:256
	v_add_u32_e32 v192, 0x10000, v142
	global_load_dwordx4 v[192:195], v192, s[66:67]
	v_add_u32_e32 v196, 0x10000, v142
	global_load_dwordx4 v[196:199], v196, s[70:71]
	v_add_u32_e32 v208, 0x10000, v142
	global_load_dwordx4 v[208:211], v208, s[66:67] offset:256
	v_add_u32_e32 v212, 0x10000, v142
	global_load_dwordx4 v[212:215], v212, s[70:71] offset:256
	s_waitcnt vmcnt(10)
	v_lshlrev_b32_e32 v156, 16, v152
	v_and_b32_e32 v157, 0xffff0000, v152
	v_lshlrev_b32_e32 v158, 16, v148
	v_and_b32_e32 v159, 0xffff0000, v148
	v_pk_fma_f32 v[124:125], v[124:125], v[156:157], v[158:159]
	v_lshlrev_b32_e32 v216, 16, v153
	v_and_b32_e32 v217, 0xffff0000, v153
	v_lshlrev_b32_e32 v218, 16, v149
	v_and_b32_e32 v219, 0xffff0000, v149
	v_pk_fma_f32 v[126:127], v[126:127], v[216:217], v[218:219]
	v_lshlrev_b32_e32 v156, 16, v154
	v_and_b32_e32 v157, 0xffff0000, v154
	v_lshlrev_b32_e32 v158, 16, v150
	v_and_b32_e32 v159, 0xffff0000, v150
	v_pk_fma_f32 v[120:121], v[120:121], v[156:157], v[158:159]
	v_lshlrev_b32_e32 v216, 16, v155
	v_and_b32_e32 v217, 0xffff0000, v155
	v_lshlrev_b32_e32 v218, 16, v151
	v_and_b32_e32 v219, 0xffff0000, v151
	v_pk_fma_f32 v[122:123], v[122:123], v[216:217], v[218:219]
	v_mov_b32_e32 v152, v142
	v_cvt_pk_bf16_f32 v148, v124, v125
	v_cvt_pk_bf16_f32 v149, v126, v127
	v_cvt_pk_bf16_f32 v150, v120, v121
	v_cvt_pk_bf16_f32 v151, v122, v123
	s_nop 0
	global_store_dwordx4 v152, v[148:151], s[82:83]
	s_nop 1
	v_add_u32_e32 v148, 0x18000, v142
	global_load_dwordx4 v[148:151], v148, s[66:67]
	v_add_u32_e32 v152, 0x18000, v142
	global_load_dwordx4 v[152:155], v152, s[70:71]
	s_waitcnt vmcnt(11)
	v_lshlrev_b32_e32 v156, 16, v172
	v_and_b32_e32 v157, 0xffff0000, v172
	v_lshlrev_b32_e32 v158, 16, v168
	v_and_b32_e32 v159, 0xffff0000, v168
	v_pk_fma_f32 v[116:117], v[116:117], v[156:157], v[158:159]
	v_lshlrev_b32_e32 v216, 16, v173
	v_and_b32_e32 v217, 0xffff0000, v173
	v_lshlrev_b32_e32 v218, 16, v169
	v_and_b32_e32 v219, 0xffff0000, v169
	v_pk_fma_f32 v[118:119], v[118:119], v[216:217], v[218:219]
	v_lshlrev_b32_e32 v156, 16, v174
	v_and_b32_e32 v157, 0xffff0000, v174
	v_lshlrev_b32_e32 v158, 16, v170
	v_and_b32_e32 v159, 0xffff0000, v170
	v_pk_fma_f32 v[112:113], v[112:113], v[156:157], v[158:159]
	v_lshlrev_b32_e32 v216, 16, v175
	v_and_b32_e32 v217, 0xffff0000, v175
	v_lshlrev_b32_e32 v218, 16, v171
	v_and_b32_e32 v219, 0xffff0000, v171
	v_pk_fma_f32 v[114:115], v[114:115], v[216:217], v[218:219]
	v_mov_b32_e32 v172, v142
	v_cvt_pk_bf16_f32 v168, v116, v117
	v_cvt_pk_bf16_f32 v169, v118, v119
	v_cvt_pk_bf16_f32 v170, v112, v113
	v_cvt_pk_bf16_f32 v171, v114, v115
	s_nop 0
	global_store_dwordx4 v172, v[168:171], s[82:83] offset:256
	s_nop 1
	v_add_u32_e32 v168, 0x18000, v142
	global_load_dwordx4 v[168:171], v168, s[66:67] offset:256
	v_add_u32_e32 v172, 0x18000, v142
	global_load_dwordx4 v[172:175], v172, s[70:71] offset:256
	s_waitcnt vmcnt(12)
	v_lshlrev_b32_e32 v156, 16, v180
	v_and_b32_e32 v157, 0xffff0000, v180
	v_lshlrev_b32_e32 v158, 16, v176
	v_and_b32_e32 v159, 0xffff0000, v176
	v_pk_fma_f32 v[108:109], v[108:109], v[156:157], v[158:159]
	v_lshlrev_b32_e32 v216, 16, v181
	v_and_b32_e32 v217, 0xffff0000, v181
	v_lshlrev_b32_e32 v218, 16, v177
	v_and_b32_e32 v219, 0xffff0000, v177
	v_pk_fma_f32 v[110:111], v[110:111], v[216:217], v[218:219]
	v_lshlrev_b32_e32 v156, 16, v182
	v_and_b32_e32 v157, 0xffff0000, v182
	v_lshlrev_b32_e32 v158, 16, v178
	v_and_b32_e32 v159, 0xffff0000, v178
	v_pk_fma_f32 v[104:105], v[104:105], v[156:157], v[158:159]
	v_lshlrev_b32_e32 v216, 16, v183
	v_and_b32_e32 v217, 0xffff0000, v183
	v_lshlrev_b32_e32 v218, 16, v179
	v_and_b32_e32 v219, 0xffff0000, v179
	v_pk_fma_f32 v[106:107], v[106:107], v[216:217], v[218:219]
	v_add_u32_e32 v180, 0x8000, v142
	v_cvt_pk_bf16_f32 v176, v108, v109
	v_cvt_pk_bf16_f32 v177, v110, v111
	v_cvt_pk_bf16_f32 v178, v104, v105
	v_cvt_pk_bf16_f32 v179, v106, v107
	s_nop 0
	global_store_dwordx4 v180, v[176:179], s[82:83]
	s_nop 1
	v_add_u32_e32 v176, 0x40000, v142
	global_load_dwordx4 v[176:179], v176, s[66:67]
	v_add_u32_e32 v180, 0x40000, v142
	global_load_dwordx4 v[180:183], v180, s[70:71]
	s_waitcnt vmcnt(13)
	v_lshlrev_b32_e32 v156, 16, v188
	v_and_b32_e32 v157, 0xffff0000, v188
	v_lshlrev_b32_e32 v158, 16, v184
	v_and_b32_e32 v159, 0xffff0000, v184
	v_pk_fma_f32 v[100:101], v[100:101], v[156:157], v[158:159]
	v_lshlrev_b32_e32 v216, 16, v189
	v_and_b32_e32 v217, 0xffff0000, v189
	v_lshlrev_b32_e32 v218, 16, v185
	v_and_b32_e32 v219, 0xffff0000, v185
	v_pk_fma_f32 v[102:103], v[102:103], v[216:217], v[218:219]
	v_lshlrev_b32_e32 v156, 16, v190
	v_and_b32_e32 v157, 0xffff0000, v190
	v_lshlrev_b32_e32 v158, 16, v186
	v_and_b32_e32 v159, 0xffff0000, v186
	v_pk_fma_f32 v[96:97], v[96:97], v[156:157], v[158:159]
	v_lshlrev_b32_e32 v216, 16, v191
	v_and_b32_e32 v217, 0xffff0000, v191
	v_lshlrev_b32_e32 v218, 16, v187
	v_and_b32_e32 v219, 0xffff0000, v187
	v_pk_fma_f32 v[98:99], v[98:99], v[216:217], v[218:219]
	v_add_u32_e32 v188, 0x8000, v142
	v_cvt_pk_bf16_f32 v184, v100, v101
	v_cvt_pk_bf16_f32 v185, v102, v103
	v_cvt_pk_bf16_f32 v186, v96, v97
	v_cvt_pk_bf16_f32 v187, v98, v99
	s_nop 0
	global_store_dwordx4 v188, v[184:187], s[82:83] offset:256
	s_nop 1
	v_add_u32_e32 v184, 0x40000, v142
	global_load_dwordx4 v[184:187], v184, s[66:67] offset:256
	v_add_u32_e32 v188, 0x40000, v142
	global_load_dwordx4 v[188:191], v188, s[70:71] offset:256
	s_waitcnt vmcnt(14)
	v_lshlrev_b32_e32 v156, 16, v196
	v_and_b32_e32 v157, 0xffff0000, v196
	v_lshlrev_b32_e32 v158, 16, v192
	v_and_b32_e32 v159, 0xffff0000, v192
	v_pk_fma_f32 v[92:93], v[92:93], v[156:157], v[158:159]
	v_lshlrev_b32_e32 v216, 16, v197
	v_and_b32_e32 v217, 0xffff0000, v197
	v_lshlrev_b32_e32 v218, 16, v193
	v_and_b32_e32 v219, 0xffff0000, v193
	v_pk_fma_f32 v[94:95], v[94:95], v[216:217], v[218:219]
	v_lshlrev_b32_e32 v156, 16, v198
	v_and_b32_e32 v157, 0xffff0000, v198
	v_lshlrev_b32_e32 v158, 16, v194
	v_and_b32_e32 v159, 0xffff0000, v194
	v_pk_fma_f32 v[88:89], v[88:89], v[156:157], v[158:159]
	v_lshlrev_b32_e32 v216, 16, v199
	v_and_b32_e32 v217, 0xffff0000, v199
	v_lshlrev_b32_e32 v218, 16, v195
	v_and_b32_e32 v219, 0xffff0000, v195
	v_pk_fma_f32 v[90:91], v[90:91], v[216:217], v[218:219]
	v_add_u32_e32 v196, 0x10000, v142
	v_cvt_pk_bf16_f32 v192, v92, v93
	v_cvt_pk_bf16_f32 v193, v94, v95
	v_cvt_pk_bf16_f32 v194, v88, v89
	v_cvt_pk_bf16_f32 v195, v90, v91
	s_nop 0
	global_store_dwordx4 v196, v[192:195], s[82:83]
	s_nop 1
	v_add_u32_e32 v192, 0x48000, v142
	global_load_dwordx4 v[192:195], v192, s[66:67]
	v_add_u32_e32 v196, 0x48000, v142
	global_load_dwordx4 v[196:199], v196, s[70:71]
	s_waitcnt vmcnt(15)
	v_lshlrev_b32_e32 v156, 16, v212
	v_and_b32_e32 v157, 0xffff0000, v212
	v_lshlrev_b32_e32 v158, 16, v208
	v_and_b32_e32 v159, 0xffff0000, v208
	v_pk_fma_f32 v[84:85], v[84:85], v[156:157], v[158:159]
	v_lshlrev_b32_e32 v216, 16, v213
	v_and_b32_e32 v217, 0xffff0000, v213
	v_lshlrev_b32_e32 v218, 16, v209
	v_and_b32_e32 v219, 0xffff0000, v209
	v_pk_fma_f32 v[86:87], v[86:87], v[216:217], v[218:219]
	v_lshlrev_b32_e32 v156, 16, v214
	v_and_b32_e32 v157, 0xffff0000, v214
	v_lshlrev_b32_e32 v158, 16, v210
	v_and_b32_e32 v159, 0xffff0000, v210
	v_pk_fma_f32 v[80:81], v[80:81], v[156:157], v[158:159]
	v_lshlrev_b32_e32 v216, 16, v215
	v_and_b32_e32 v217, 0xffff0000, v215
	v_lshlrev_b32_e32 v218, 16, v211
	v_and_b32_e32 v219, 0xffff0000, v211
	v_pk_fma_f32 v[82:83], v[82:83], v[216:217], v[218:219]
	v_add_u32_e32 v212, 0x10000, v142
	v_cvt_pk_bf16_f32 v208, v84, v85
	v_cvt_pk_bf16_f32 v209, v86, v87
	v_cvt_pk_bf16_f32 v210, v80, v81
	v_cvt_pk_bf16_f32 v211, v82, v83
	s_nop 0
	global_store_dwordx4 v212, v[208:211], s[82:83] offset:256
	s_nop 1
	v_add_u32_e32 v208, 0x48000, v142
	global_load_dwordx4 v[208:211], v208, s[66:67] offset:256
	v_add_u32_e32 v212, 0x48000, v142
	global_load_dwordx4 v[212:215], v212, s[70:71] offset:256
	s_waitcnt vmcnt(15)
	v_lshlrev_b32_e32 v156, 16, v152
	v_and_b32_e32 v157, 0xffff0000, v152
	v_lshlrev_b32_e32 v158, 16, v148
	v_and_b32_e32 v159, 0xffff0000, v148
	v_pk_fma_f32 v[76:77], v[76:77], v[156:157], v[158:159]
	v_lshlrev_b32_e32 v216, 16, v153
	v_and_b32_e32 v217, 0xffff0000, v153
	v_lshlrev_b32_e32 v218, 16, v149
	v_and_b32_e32 v219, 0xffff0000, v149
	v_pk_fma_f32 v[78:79], v[78:79], v[216:217], v[218:219]
	v_lshlrev_b32_e32 v156, 16, v154
	v_and_b32_e32 v157, 0xffff0000, v154
	v_lshlrev_b32_e32 v158, 16, v150
	v_and_b32_e32 v159, 0xffff0000, v150
	v_pk_fma_f32 v[72:73], v[72:73], v[156:157], v[158:159]
	v_lshlrev_b32_e32 v216, 16, v155
	v_and_b32_e32 v217, 0xffff0000, v155
	v_lshlrev_b32_e32 v218, 16, v151
	v_and_b32_e32 v219, 0xffff0000, v151
	v_pk_fma_f32 v[74:75], v[74:75], v[216:217], v[218:219]
	v_add_u32_e32 v152, 0x18000, v142
	v_cvt_pk_bf16_f32 v148, v76, v77
	v_cvt_pk_bf16_f32 v149, v78, v79
	v_cvt_pk_bf16_f32 v150, v72, v73
	v_cvt_pk_bf16_f32 v151, v74, v75
	s_nop 0
	global_store_dwordx4 v152, v[148:151], s[82:83]
	s_nop 1
	v_add_u32_e32 v148, 0x50000, v142
	global_load_dwordx4 v[148:151], v148, s[66:67]
	v_add_u32_e32 v152, 0x50000, v142
	global_load_dwordx4 v[152:155], v152, s[70:71]
	s_waitcnt vmcnt(15)
	v_lshlrev_b32_e32 v156, 16, v172
	v_and_b32_e32 v157, 0xffff0000, v172
	v_lshlrev_b32_e32 v158, 16, v168
	v_and_b32_e32 v159, 0xffff0000, v168
	v_pk_fma_f32 v[68:69], v[68:69], v[156:157], v[158:159]
	v_lshlrev_b32_e32 v216, 16, v173
	v_and_b32_e32 v217, 0xffff0000, v173
	v_lshlrev_b32_e32 v218, 16, v169
	v_and_b32_e32 v219, 0xffff0000, v169
	v_pk_fma_f32 v[70:71], v[70:71], v[216:217], v[218:219]
	v_lshlrev_b32_e32 v156, 16, v174
	v_and_b32_e32 v157, 0xffff0000, v174
	v_lshlrev_b32_e32 v158, 16, v170
	v_and_b32_e32 v159, 0xffff0000, v170
	v_pk_fma_f32 v[64:65], v[64:65], v[156:157], v[158:159]
	v_lshlrev_b32_e32 v216, 16, v175
	v_and_b32_e32 v217, 0xffff0000, v175
	v_lshlrev_b32_e32 v218, 16, v171
	v_and_b32_e32 v219, 0xffff0000, v171
	v_pk_fma_f32 v[66:67], v[66:67], v[216:217], v[218:219]
	v_add_u32_e32 v172, 0x18000, v142
	v_cvt_pk_bf16_f32 v168, v68, v69
	v_cvt_pk_bf16_f32 v169, v70, v71
	v_cvt_pk_bf16_f32 v170, v64, v65
	v_cvt_pk_bf16_f32 v171, v66, v67
	s_nop 0
	global_store_dwordx4 v172, v[168:171], s[82:83] offset:256
	s_nop 1
	v_add_u32_e32 v168, 0x50000, v142
	global_load_dwordx4 v[168:171], v168, s[66:67] offset:256
	v_add_u32_e32 v172, 0x50000, v142
	global_load_dwordx4 v[172:175], v172, s[70:71] offset:256
	s_waitcnt vmcnt(15)
	v_lshlrev_b32_e32 v156, 16, v180
	v_and_b32_e32 v157, 0xffff0000, v180
	v_lshlrev_b32_e32 v158, 16, v176
	v_and_b32_e32 v159, 0xffff0000, v176
	v_pk_fma_f32 v[60:61], v[60:61], v[156:157], v[158:159]
	v_lshlrev_b32_e32 v216, 16, v181
	v_and_b32_e32 v217, 0xffff0000, v181
	v_lshlrev_b32_e32 v218, 16, v177
	v_and_b32_e32 v219, 0xffff0000, v177
	v_pk_fma_f32 v[62:63], v[62:63], v[216:217], v[218:219]
	v_lshlrev_b32_e32 v156, 16, v182
	v_and_b32_e32 v157, 0xffff0000, v182
	v_lshlrev_b32_e32 v158, 16, v178
	v_and_b32_e32 v159, 0xffff0000, v178
	v_pk_fma_f32 v[56:57], v[56:57], v[156:157], v[158:159]
	v_lshlrev_b32_e32 v216, 16, v183
	v_and_b32_e32 v217, 0xffff0000, v183
	v_lshlrev_b32_e32 v218, 16, v179
	v_and_b32_e32 v219, 0xffff0000, v179
	v_pk_fma_f32 v[58:59], v[58:59], v[216:217], v[218:219]
	v_add_u32_e32 v180, 0x40000, v142
	v_cvt_pk_bf16_f32 v176, v60, v61
	v_cvt_pk_bf16_f32 v177, v62, v63
	v_cvt_pk_bf16_f32 v178, v56, v57
	v_cvt_pk_bf16_f32 v179, v58, v59
	s_nop 0
	global_store_dwordx4 v180, v[176:179], s[82:83]
	s_nop 1
	v_add_u32_e32 v176, 0x58000, v142
	global_load_dwordx4 v[176:179], v176, s[66:67]
	v_add_u32_e32 v180, 0x58000, v142
	global_load_dwordx4 v[180:183], v180, s[70:71]
	s_waitcnt vmcnt(15)
	v_lshlrev_b32_e32 v156, 16, v188
	v_and_b32_e32 v157, 0xffff0000, v188
	v_lshlrev_b32_e32 v158, 16, v184
	v_and_b32_e32 v159, 0xffff0000, v184
	v_pk_fma_f32 v[52:53], v[52:53], v[156:157], v[158:159]
	v_lshlrev_b32_e32 v216, 16, v189
	v_and_b32_e32 v217, 0xffff0000, v189
	v_lshlrev_b32_e32 v218, 16, v185
	v_and_b32_e32 v219, 0xffff0000, v185
	v_pk_fma_f32 v[54:55], v[54:55], v[216:217], v[218:219]
	v_lshlrev_b32_e32 v156, 16, v190
	v_and_b32_e32 v157, 0xffff0000, v190
	v_lshlrev_b32_e32 v158, 16, v186
	v_and_b32_e32 v159, 0xffff0000, v186
	v_pk_fma_f32 v[48:49], v[48:49], v[156:157], v[158:159]
	v_lshlrev_b32_e32 v216, 16, v191
	v_and_b32_e32 v217, 0xffff0000, v191
	v_lshlrev_b32_e32 v218, 16, v187
	v_and_b32_e32 v219, 0xffff0000, v187
	v_pk_fma_f32 v[50:51], v[50:51], v[216:217], v[218:219]
	v_add_u32_e32 v188, 0x40000, v142
	v_cvt_pk_bf16_f32 v184, v52, v53
	v_cvt_pk_bf16_f32 v185, v54, v55
	v_cvt_pk_bf16_f32 v186, v48, v49
	v_cvt_pk_bf16_f32 v187, v50, v51
	s_nop 0
	global_store_dwordx4 v188, v[184:187], s[82:83] offset:256
	s_nop 1
	v_add_u32_e32 v184, 0x58000, v142
	global_load_dwordx4 v[184:187], v184, s[66:67] offset:256
	v_add_u32_e32 v188, 0x58000, v142
	global_load_dwordx4 v[188:191], v188, s[70:71] offset:256
	s_waitcnt vmcnt(15)
	v_lshlrev_b32_e32 v156, 16, v196
	v_and_b32_e32 v157, 0xffff0000, v196
	v_lshlrev_b32_e32 v158, 16, v192
	v_and_b32_e32 v159, 0xffff0000, v192
	v_pk_fma_f32 v[44:45], v[44:45], v[156:157], v[158:159]
	v_lshlrev_b32_e32 v216, 16, v197
	v_and_b32_e32 v217, 0xffff0000, v197
	v_lshlrev_b32_e32 v218, 16, v193
	v_and_b32_e32 v219, 0xffff0000, v193
	v_pk_fma_f32 v[46:47], v[46:47], v[216:217], v[218:219]
	v_lshlrev_b32_e32 v156, 16, v198
	v_and_b32_e32 v157, 0xffff0000, v198
	v_lshlrev_b32_e32 v158, 16, v194
	v_and_b32_e32 v159, 0xffff0000, v194
	v_pk_fma_f32 v[40:41], v[40:41], v[156:157], v[158:159]
	v_lshlrev_b32_e32 v216, 16, v199
	v_and_b32_e32 v217, 0xffff0000, v199
	v_lshlrev_b32_e32 v218, 16, v195
	v_and_b32_e32 v219, 0xffff0000, v195
	v_pk_fma_f32 v[42:43], v[42:43], v[216:217], v[218:219]
	v_add_u32_e32 v196, 0x48000, v142
	v_cvt_pk_bf16_f32 v192, v44, v45
	v_cvt_pk_bf16_f32 v193, v46, v47
	v_cvt_pk_bf16_f32 v194, v40, v41
	v_cvt_pk_bf16_f32 v195, v42, v43
	s_nop 0
	global_store_dwordx4 v196, v[192:195], s[82:83]
	s_waitcnt vmcnt(13)
	v_lshlrev_b32_e32 v156, 16, v212
	v_and_b32_e32 v157, 0xffff0000, v212
	v_lshlrev_b32_e32 v158, 16, v208
	v_and_b32_e32 v159, 0xffff0000, v208
	v_pk_fma_f32 v[36:37], v[36:37], v[156:157], v[158:159]
	v_lshlrev_b32_e32 v216, 16, v213
	v_and_b32_e32 v217, 0xffff0000, v213
	v_lshlrev_b32_e32 v218, 16, v209
	v_and_b32_e32 v219, 0xffff0000, v209
	v_pk_fma_f32 v[38:39], v[38:39], v[216:217], v[218:219]
	v_lshlrev_b32_e32 v156, 16, v214
	v_and_b32_e32 v157, 0xffff0000, v214
	v_lshlrev_b32_e32 v158, 16, v210
	v_and_b32_e32 v159, 0xffff0000, v210
	v_pk_fma_f32 v[32:33], v[32:33], v[156:157], v[158:159]
	v_lshlrev_b32_e32 v216, 16, v215
	v_and_b32_e32 v217, 0xffff0000, v215
	v_lshlrev_b32_e32 v218, 16, v211
	v_and_b32_e32 v219, 0xffff0000, v211
	v_pk_fma_f32 v[34:35], v[34:35], v[216:217], v[218:219]
	v_add_u32_e32 v212, 0x48000, v142
	v_cvt_pk_bf16_f32 v208, v36, v37
	v_cvt_pk_bf16_f32 v209, v38, v39
	v_cvt_pk_bf16_f32 v210, v32, v33
	v_cvt_pk_bf16_f32 v211, v34, v35
	s_nop 0
	global_store_dwordx4 v212, v[208:211], s[82:83] offset:256
	s_waitcnt vmcnt(11)
	v_lshlrev_b32_e32 v156, 16, v152
	v_and_b32_e32 v157, 0xffff0000, v152
	v_lshlrev_b32_e32 v158, 16, v148
	v_and_b32_e32 v159, 0xffff0000, v148
	v_pk_fma_f32 v[28:29], v[28:29], v[156:157], v[158:159]
	v_lshlrev_b32_e32 v216, 16, v153
	v_and_b32_e32 v217, 0xffff0000, v153
	v_lshlrev_b32_e32 v218, 16, v149
	v_and_b32_e32 v219, 0xffff0000, v149
	v_pk_fma_f32 v[30:31], v[30:31], v[216:217], v[218:219]
	v_lshlrev_b32_e32 v156, 16, v154
	v_and_b32_e32 v157, 0xffff0000, v154
	v_lshlrev_b32_e32 v158, 16, v150
	v_and_b32_e32 v159, 0xffff0000, v150
	v_pk_fma_f32 v[24:25], v[24:25], v[156:157], v[158:159]
	v_lshlrev_b32_e32 v216, 16, v155
	v_and_b32_e32 v217, 0xffff0000, v155
	v_lshlrev_b32_e32 v218, 16, v151
	v_and_b32_e32 v219, 0xffff0000, v151
	v_pk_fma_f32 v[26:27], v[26:27], v[216:217], v[218:219]
	v_add_u32_e32 v152, 0x50000, v142
	v_cvt_pk_bf16_f32 v148, v28, v29
	v_cvt_pk_bf16_f32 v149, v30, v31
	v_cvt_pk_bf16_f32 v150, v24, v25
	v_cvt_pk_bf16_f32 v151, v26, v27
	s_nop 0
	global_store_dwordx4 v152, v[148:151], s[82:83]
	s_waitcnt vmcnt(9)
	v_lshlrev_b32_e32 v156, 16, v172
	v_and_b32_e32 v157, 0xffff0000, v172
	v_lshlrev_b32_e32 v158, 16, v168
	v_and_b32_e32 v159, 0xffff0000, v168
	v_pk_fma_f32 v[20:21], v[20:21], v[156:157], v[158:159]
	v_lshlrev_b32_e32 v216, 16, v173
	v_and_b32_e32 v217, 0xffff0000, v173
	v_lshlrev_b32_e32 v218, 16, v169
	v_and_b32_e32 v219, 0xffff0000, v169
	v_pk_fma_f32 v[22:23], v[22:23], v[216:217], v[218:219]
	v_lshlrev_b32_e32 v156, 16, v174
	v_and_b32_e32 v157, 0xffff0000, v174
	v_lshlrev_b32_e32 v158, 16, v170
	v_and_b32_e32 v159, 0xffff0000, v170
	v_pk_fma_f32 v[16:17], v[16:17], v[156:157], v[158:159]
	v_lshlrev_b32_e32 v216, 16, v175
	v_and_b32_e32 v217, 0xffff0000, v175
	v_lshlrev_b32_e32 v218, 16, v171
	v_and_b32_e32 v219, 0xffff0000, v171
	v_pk_fma_f32 v[18:19], v[18:19], v[216:217], v[218:219]
	v_add_u32_e32 v172, 0x50000, v142
	v_cvt_pk_bf16_f32 v168, v20, v21
	v_cvt_pk_bf16_f32 v169, v22, v23
	v_cvt_pk_bf16_f32 v170, v16, v17
	v_cvt_pk_bf16_f32 v171, v18, v19
	s_nop 0
	global_store_dwordx4 v172, v[168:171], s[82:83] offset:256
	s_waitcnt vmcnt(7)
	v_lshlrev_b32_e32 v156, 16, v180
	v_and_b32_e32 v157, 0xffff0000, v180
	v_lshlrev_b32_e32 v158, 16, v176
	v_and_b32_e32 v159, 0xffff0000, v176
	v_pk_fma_f32 v[12:13], v[12:13], v[156:157], v[158:159]
	v_lshlrev_b32_e32 v216, 16, v181
	v_and_b32_e32 v217, 0xffff0000, v181
	v_lshlrev_b32_e32 v218, 16, v177
	v_and_b32_e32 v219, 0xffff0000, v177
	v_pk_fma_f32 v[14:15], v[14:15], v[216:217], v[218:219]
	v_lshlrev_b32_e32 v156, 16, v182
	v_and_b32_e32 v157, 0xffff0000, v182
	v_lshlrev_b32_e32 v158, 16, v178
	v_and_b32_e32 v159, 0xffff0000, v178
	v_pk_fma_f32 v[8:9], v[8:9], v[156:157], v[158:159]
	v_lshlrev_b32_e32 v216, 16, v183
	v_and_b32_e32 v217, 0xffff0000, v183
	v_lshlrev_b32_e32 v218, 16, v179
	v_and_b32_e32 v219, 0xffff0000, v179
	v_pk_fma_f32 v[10:11], v[10:11], v[216:217], v[218:219]
	v_add_u32_e32 v180, 0x58000, v142
	v_cvt_pk_bf16_f32 v176, v12, v13
	v_cvt_pk_bf16_f32 v177, v14, v15
	v_cvt_pk_bf16_f32 v178, v8, v9
	v_cvt_pk_bf16_f32 v179, v10, v11
	s_nop 0
	global_store_dwordx4 v180, v[176:179], s[82:83]
	s_waitcnt vmcnt(5)
	v_lshlrev_b32_e32 v156, 16, v188
	v_and_b32_e32 v157, 0xffff0000, v188
	v_lshlrev_b32_e32 v158, 16, v184
	v_and_b32_e32 v159, 0xffff0000, v184
	v_pk_fma_f32 v[4:5], v[4:5], v[156:157], v[158:159]
	v_lshlrev_b32_e32 v216, 16, v189
	v_and_b32_e32 v217, 0xffff0000, v189
	v_lshlrev_b32_e32 v218, 16, v185
	v_and_b32_e32 v219, 0xffff0000, v185
	v_pk_fma_f32 v[6:7], v[6:7], v[216:217], v[218:219]
	v_lshlrev_b32_e32 v156, 16, v190
	v_and_b32_e32 v157, 0xffff0000, v190
	v_lshlrev_b32_e32 v158, 16, v186
	v_and_b32_e32 v159, 0xffff0000, v186
	v_pk_fma_f32 v[0:1], v[0:1], v[156:157], v[158:159]
	v_lshlrev_b32_e32 v216, 16, v191
	v_and_b32_e32 v217, 0xffff0000, v191
	v_lshlrev_b32_e32 v218, 16, v187
	v_and_b32_e32 v219, 0xffff0000, v187
	v_pk_fma_f32 v[2:3], v[2:3], v[216:217], v[218:219]
	v_add_u32_e32 v188, 0x58000, v142
	v_cvt_pk_bf16_f32 v184, v4, v5
	v_cvt_pk_bf16_f32 v185, v6, v7
	v_cvt_pk_bf16_f32 v186, v0, v1
	v_cvt_pk_bf16_f32 v187, v2, v3
	s_nop 0
	global_store_dwordx4 v188, v[184:187], s[82:83] offset:256
	s_cbranch_vccnz .LBB0_529
	s_andn2_b64 vcc, exec, s[0:1]
	s_cbranch_vccnz .LBB0_528
	s_barrier
	s_branch .LBB0_528
